# AB post phase row loop: six column-segment loads issued together at row top (own regs, lane-masked), copies at use sites behind counted waits
# speedup vs baseline: 1.0179x; 1.0018x over previous
; __device__ __forceinline__ float bf2f(unsigned h) { return __uint_as_float(h << 16); }
; __device__ __forceinline__ unsigned pk2(float lo, float hi) { f32x2 v = {lo, hi}; bf16x2_t b = __builtin_convertvector(v, bf16x2_t); return __builtin_bit_cast(unsigned, b); }
; __global__ void __launch_bounds__(512, 2) fwd_kernel(Params P) {
;     ...
;         for (int row = gw; row < MR; row += NGW) {
;             bf16_t* pr = BIG + (size_t)row * PROJ_LD;
;             const int pos = row_pos(row);
;             float cs[8], sn[8];
; #pragma unroll
;             for (int i = 0; i < 8; ++i) { const float inv = __builtin_amdgcn_exp2f(-(float)(dsub + i) * (13.287712379549449f / 32.0f)); const float ang_ = (float)pos * inv; sn[i] = __sinf(ang_); cs[i] = __cosf(ang_); }
;             { const u32x4 raw = *(const u32x4*)(pr + lane * 8); float x[8], y[8];
; #pragma unroll
;               for (int i = 0; i < 4; ++i) { x[2 * i] = bf2f(raw[i] & 0xffff); x[2 * i + 1] = bf2f(raw[i] >> 16); }
; #pragma unroll
;               for (int i = 0; i < 8; ++i) { const float o = __shfl_xor(x[i], 4); y[i] = (ishi ? (x[i] * cs[i] + o * sn[i]) : (x[i] * cs[i] - o * sn[i])) * (0.125f * LOG2E); }
;               u32x4 wv; wv.x = pk2(y[0], y[1]); wv.y = pk2(y[2], y[3]); wv.z = pk2(y[4], y[5]); wv.w = pk2(y[6], y[7]); *(u32x4*)(pr + lane * 8) = wv; }
;             { const u32x4 raw = *(const u32x4*)(pr + 512 + lane * 8); float x[8], y[8];
; #pragma unroll
;               for (int i = 0; i < 4; ++i) { x[2 * i] = bf2f(raw[i] & 0xffff); x[2 * i + 1] = bf2f(raw[i] >> 16); }
; #pragma unroll
;               for (int i = 0; i < 8; ++i) { const float o = __shfl_xor(x[i], 4); y[i] = ishi ? (x[i] * cs[i] + o * sn[i]) : (x[i] * cs[i] - o * sn[i]); }
;               float* fo = OUT + O_AK + (size_t)row * 512 + lane * 8; __builtin_nontemporal_store((f32x4){y[0], y[1], y[2], y[3]}, (f32x4*)fo); __builtin_nontemporal_store((f32x4){y[4], y[5], y[6], y[7]}, (f32x4*)(fo + 4));
;               u32x4 wv; wv.x = pk2(y[0], y[1]); wv.y = pk2(y[2], y[3]); wv.z = pk2(y[4], y[5]); wv.w = pk2(y[6], y[7]);
;               if (row < NP) *(u32x4*)(pr + 512 + lane * 8) = wv;
;               else { const int bs = (row - NP) >> 4, t = (row - NP) & 15; *(u32x4*)(KAS + ((size_t)bs * LKSP + 1024 + t) * 512 + lane * 8) = wv; } }
.LBB0_515:
	s_cmpk_gt_i32 s60, 0x7fff
	s_cselect_b64 s[14:15], -1, 0
	s_and_b32 s70, s60, 15
	s_and_b32 s3, s60, 0x7ff
	s_or_b32 s4, s70, 0x400
	s_cmp_lt_i32 s60, 0x8000
	s_cselect_b32 s3, s3, s4
	s_waitcnt lgkmcnt(7)
	v_cvt_f32_u32_e32 v0, s3
	s_mov_b32 s3, 0x8080000
	s_mov_b64 s[12:13], -1
	v_mul_f32_e32 v1, v58, v0
	v_mul_f32_e32 v1, 0.15915494, v1
	v_sin_f32_e32 v40, v1
	v_cos_f32_e32 v36, v1
	v_mul_f32_e32 v1, v59, v0
	v_mul_f32_e32 v1, 0.15915494, v1
	v_sin_f32_e32 v39, v1
	v_cos_f32_e32 v38, v1
	v_mul_f32_e32 v1, v60, v0
	v_mul_f32_e32 v1, 0.15915494, v1
	v_sin_f32_e32 v34, v1
	v_cos_f32_e32 v32, v1
	v_mul_f32_e32 v1, v61, v0
	v_mul_f32_e32 v1, 0.15915494, v1
	v_sin_f32_e32 v35, v1
	v_cos_f32_e32 v33, v1
	v_mul_f32_e32 v1, v62, v0
	v_mul_f32_e32 v1, 0.15915494, v1
	v_sin_f32_e32 v30, v1
	v_cos_f32_e32 v28, v1
	v_mul_f32_e32 v1, v63, v0
	v_mul_f32_e32 v1, 0.15915494, v1
	v_sin_f32_e32 v31, v1
	v_cos_f32_e32 v29, v1
	v_mul_f32_e32 v1, v64, v0
	v_mul_f32_e32 v0, v65, v0
	v_mul_f32_e32 v1, 0.15915494, v1
	v_mul_f32_e32 v0, 0.15915494, v0
	v_sin_f32_e32 v26, v1
	v_cos_f32_e32 v24, v1
	v_sin_f32_e32 v27, v0
	v_cos_f32_e32 v25, v0
	global_load_dwordx4 v[72:75], v[22:23], off
	global_load_dwordx4 v[76:79], v[22:23], off offset:1024
	global_load_dwordx4 v[82:85], v[22:23], off offset:2048
	v_mov_b32_e32 v86, 0
	v_mov_b32_e32 v87, 0
	v_mov_b32_e32 v88, 0
	v_mov_b32_e32 v89, 0
	v_mov_b32_e32 v90, 0
	v_mov_b32_e32 v91, 0
	v_mov_b32_e32 v92, 0
	v_mov_b32_e32 v93, 0
	v_mov_b32_e32 v94, 0
	v_mov_b32_e32 v95, 0
	v_mov_b32_e32 v96, 0
	v_mov_b32_e32 v97, 0
	s_mov_b32 s98, 0x1000
	s_mov_b32 s99, 0
	v_lshl_add_u64 v[104:105], v[22:23], 0, s[98:99]
	s_mov_b64 s[100:101], exec
	s_and_b64 exec, s[100:101], s[6:7]
	global_load_dwordx4 v[86:89], v[22:23], off offset:3072
	s_and_b64 exec, s[100:101], s[8:9]
	global_load_dwordx4 v[90:93], v[22:23], off offset:3840
	s_and_b64 exec, s[100:101], s[10:11]
	global_load_dwordx4 v[94:97], v[104:105], off offset:256
	s_mov_b64 exec, s[100:101]
	v_mov_b32_e32 v41, v39
	v_mov_b32_e32 v37, v38
	s_waitcnt vmcnt(5)
	s_nop 1
	v_mov_b32_e32 v0, v72
	v_mov_b32_e32 v1, v73
	v_mov_b32_e32 v2, v74
	v_mov_b32_e32 v3, v75
	v_lshlrev_b32_e32 v5, 16, v0
	v_and_b32_e32 v4, 0xffff0000, v0
	ds_bpermute_b32 v0, v52, v5
	s_waitcnt lgkmcnt(0)
	v_mul_f32_e32 v0, v40, v0
	v_cndmask_b32_e64 v6, v0, -v0, s[0:1]
	v_fmac_f32_e32 v6, v36, v5
	ds_bpermute_b32 v5, v52, v4
	s_waitcnt lgkmcnt(0)
	v_pk_mul_f32 v[4:5], v[38:39], v[4:5]
	s_nop 0
	v_add_f32_e32 v0, v4, v5
	v_sub_f32_e32 v4, v4, v5
	v_cndmask_b32_e64 v7, v0, v4, s[0:1]
	v_lshlrev_b32_e32 v0, 16, v1
	v_and_b32_e32 v1, 0xffff0000, v1
	v_pk_mul_f32 v[4:5], v[6:7], s[58:59] op_sel_hi:[1,0]
	ds_bpermute_b32 v6, v52, v0
	ds_bpermute_b32 v7, v52, v1
	s_waitcnt lgkmcnt(0)
	v_pk_mul_f32 v[6:7], v[34:35], v[6:7]
	s_nop 0
	v_pk_fma_f32 v[42:43], v[32:33], v[0:1], v[6:7]
	v_pk_fma_f32 v[0:1], v[32:33], v[0:1], v[6:7] neg_lo:[0,0,1] neg_hi:[0,0,1]
	s_nop 0
	v_cndmask_b32_e64 v1, v43, v1, s[0:1]
	v_cndmask_b32_e64 v0, v42, v0, s[0:1]
	v_pk_mul_f32 v[6:7], v[0:1], s[58:59] op_sel_hi:[1,0]
	v_lshlrev_b32_e32 v0, 16, v2
	v_and_b32_e32 v1, 0xffff0000, v2
	ds_bpermute_b32 v42, v52, v0
	ds_bpermute_b32 v43, v52, v1
	s_waitcnt lgkmcnt(0)
	v_pk_mul_f32 v[42:43], v[30:31], v[42:43]
	s_nop 0
	v_pk_fma_f32 v[44:45], v[28:29], v[0:1], v[42:43]
	v_pk_fma_f32 v[0:1], v[28:29], v[0:1], v[42:43] neg_lo:[0,0,1] neg_hi:[0,0,1]
	s_nop 0
	v_cndmask_b32_e64 v1, v45, v1, s[0:1]
	v_cndmask_b32_e64 v0, v44, v0, s[0:1]
	v_pk_mul_f32 v[42:43], v[0:1], s[58:59] op_sel_hi:[1,0]
	v_lshlrev_b32_e32 v0, 16, v3
	v_and_b32_e32 v1, 0xffff0000, v3
	ds_bpermute_b32 v2, v52, v0
	ds_bpermute_b32 v3, v52, v1
	s_waitcnt lgkmcnt(0)
	v_pk_mul_f32 v[2:3], v[26:27], v[2:3]
	s_nop 0
	v_pk_fma_f32 v[44:45], v[24:25], v[0:1], v[2:3]
	v_pk_fma_f32 v[0:1], v[24:25], v[0:1], v[2:3] neg_lo:[0,0,1] neg_hi:[0,0,1]
	v_cvt_pk_bf16_f32 v2, v42, v43
	v_cndmask_b32_e64 v1, v45, v1, s[0:1]
	v_cndmask_b32_e64 v0, v44, v0, s[0:1]
	v_pk_mul_f32 v[44:45], v[0:1], s[58:59] op_sel_hi:[1,0]
	v_cvt_pk_bf16_f32 v0, v4, v5
	v_cvt_pk_bf16_f32 v1, v6, v7
	v_cvt_pk_bf16_f32 v3, v44, v45
	global_store_dwordx4 v[22:23], v[0:3], off
	s_waitcnt vmcnt(4)
	s_nop 1
	v_mov_b32_e32 v0, v76
	v_mov_b32_e32 v1, v77
	v_mov_b32_e32 v2, v78
	v_mov_b32_e32 v3, v79
	v_lshlrev_b32_e32 v4, 16, v0
	v_and_b32_e32 v5, 0xffff0000, v0
	ds_bpermute_b32 v6, v52, v4
	ds_bpermute_b32 v7, v52, v5
	v_lshlrev_b32_e32 v0, 16, v1
	v_and_b32_e32 v1, 0xffff0000, v1
	s_waitcnt lgkmcnt(0)
	v_pk_mul_f32 v[6:7], v[40:41], v[6:7]
	s_nop 0
	v_pk_fma_f32 v[42:43], v[36:37], v[4:5], v[6:7]
	v_pk_fma_f32 v[4:5], v[36:37], v[4:5], v[6:7] neg_lo:[0,0,1] neg_hi:[0,0,1]
	s_nop 0
	v_cndmask_b32_e64 v43, v43, v5, s[0:1]
	v_cndmask_b32_e64 v42, v42, v4, s[0:1]
	ds_bpermute_b32 v4, v52, v0
	ds_bpermute_b32 v5, v52, v1
	s_waitcnt lgkmcnt(0)
	v_pk_mul_f32 v[4:5], v[34:35], v[4:5]
	s_nop 0
	v_pk_fma_f32 v[6:7], v[32:33], v[0:1], v[4:5]
	v_pk_fma_f32 v[0:1], v[32:33], v[0:1], v[4:5] neg_lo:[0,0,1] neg_hi:[0,0,1]
	s_nop 0
	v_cndmask_b32_e64 v45, v7, v1, s[0:1]
	v_cndmask_b32_e64 v44, v6, v0, s[0:1]
	v_lshlrev_b32_e32 v0, 16, v2
	v_and_b32_e32 v1, 0xffff0000, v2
	ds_bpermute_b32 v4, v52, v0
	ds_bpermute_b32 v5, v52, v1
	s_waitcnt lgkmcnt(0)
	v_pk_mul_f32 v[4:5], v[30:31], v[4:5]
	s_nop 0
	v_pk_fma_f32 v[6:7], v[28:29], v[0:1], v[4:5]
	v_pk_fma_f32 v[0:1], v[28:29], v[0:1], v[4:5] neg_lo:[0,0,1] neg_hi:[0,0,1]
	s_nop 0
	v_cndmask_b32_e64 v47, v7, v1, s[0:1]
	v_cndmask_b32_e64 v46, v6, v0, s[0:1]
	v_lshlrev_b32_e32 v0, 16, v3
	v_and_b32_e32 v1, 0xffff0000, v3
	ds_bpermute_b32 v2, v52, v0
	ds_bpermute_b32 v3, v52, v1
	s_waitcnt lgkmcnt(0)
	v_pk_mul_f32 v[2:3], v[26:27], v[2:3]
	s_nop 0
	v_pk_fma_f32 v[4:5], v[24:25], v[0:1], v[2:3]
	v_pk_fma_f32 v[0:1], v[24:25], v[0:1], v[2:3] neg_lo:[0,0,1] neg_hi:[0,0,1]
	v_cvt_pk_bf16_f32 v2, v46, v47
	v_cndmask_b32_e64 v49, v5, v1, s[0:1]
	v_cndmask_b32_e64 v48, v4, v0, s[0:1]
	v_lshl_add_u64 v[4:5], s[52:53], 0, v[12:13]
	v_add_co_u32_e32 v0, vcc, s3, v4
	v_cvt_pk_bf16_f32 v3, v48, v49
	s_nop 0
	v_addc_co_u32_e32 v1, vcc, 0, v5, vcc
	global_store_dwordx4 v[0:1], v[42:45], off nt
	global_store_dwordx4 v[0:1], v[46:49], off offset:16 nt
	v_cvt_pk_bf16_f32 v0, v42, v43
	v_cvt_pk_bf16_f32 v1, v44, v45
	s_and_b64 vcc, exec, s[14:15]
	s_cbranch_vccz .LBB0_517
	s_add_i32 s3, s60, 0xffff8000
	s_lshr_b32 s3, s3, 4
	s_mul_hi_u32 s5, s3, 0x440
	s_mulk_i32 s3, 0x440
	s_or_b32 s4, s3, s70
	s_lshl_b64 s[4:5], s[4:5], 10
	v_lshl_add_u64 v[6:7], v[8:9], 0, s[4:5]
	v_add_co_u32_e32 v6, vcc, 0x100000, v6
	s_mov_b64 s[12:13], 0
	s_nop 0
	v_addc_co_u32_e32 v7, vcc, 0, v7, vcc
	global_store_dwordx4 v[6:7], v[0:3], off

; __device__ __forceinline__ float bf2f(unsigned h) { return __uint_as_float(h << 16); }
; __global__ void __launch_bounds__(512, 2) fwd_kernel(Params P) {
;     ...
;             { const u32x4 raw = *(const u32x4*)(pr + 1024 + lane * 8); float x[8];
; #pragma unroll
;               for (int i = 0; i < 4; ++i) { x[2 * i] = bf2f(raw[i] & 0xffff); x[2 * i + 1] = bf2f(raw[i] >> 16); }
;               float* fo = OUT + O_AV + (size_t)row * 512 + lane * 8; __builtin_nontemporal_store((f32x4){x[0], x[1], x[2], x[3]}, (f32x4*)fo); __builtin_nontemporal_store((f32x4){x[4], x[5], x[6], x[7]}, (f32x4*)(fo + 4));
;               if (row >= NP) { const int bs = (row - NP) >> 4, t = (row - NP) & 15; *(u32x4*)(VAS + ((size_t)bs * LKSP + 1024 + t) * 512 + lane * 8) = raw; } }
.LBB0_519:
	v_add_co_u32_e32 v46, vcc, 0xc0c0000, v4
	s_cmp_lt_i32 s60, 0x8000
	s_nop 0
	v_addc_co_u32_e32 v47, vcc, 0, v5, vcc
	s_waitcnt vmcnt(3)
	s_nop 1
	v_mov_b32_e32 v0, v82
	v_mov_b32_e32 v1, v83
	v_mov_b32_e32 v2, v84
	v_mov_b32_e32 v3, v85
	v_lshlrev_b32_e32 v4, 16, v0
	v_and_b32_e32 v5, 0xffff0000, v0
	v_lshlrev_b32_e32 v6, 16, v1
	v_and_b32_e32 v7, 0xffff0000, v1
	v_lshlrev_b32_e32 v42, 16, v2
	v_and_b32_e32 v43, 0xffff0000, v2
	v_lshlrev_b32_e32 v44, 16, v3
	v_and_b32_e32 v45, 0xffff0000, v3
	global_store_dwordx4 v[46:47], v[4:7], off nt
	global_store_dwordx4 v[46:47], v[42:45], off offset:16 nt
	s_cbranch_scc1 .LBB0_521
	s_add_i32 s3, s60, 0xffff8000
	s_lshr_b32 s3, s3, 4
	s_mul_hi_u32 s5, s3, 0x440
	s_mulk_i32 s3, 0x440
	s_or_b32 s4, s3, s70
	s_lshl_b64 s[4:5], s[4:5], 10
	v_lshl_add_u64 v[4:5], v[10:11], 0, s[4:5]
	v_add_co_u32_e32 v4, vcc, 0x100000, v4
	s_nop 1
	v_addc_co_u32_e32 v5, vcc, 0, v5, vcc
	global_store_dwordx4 v[4:5], v[0:3], off

; __device__ __forceinline__ float bf2f(unsigned h) { return __uint_as_float(h << 16); }
; __device__ __forceinline__ unsigned pk2(float lo, float hi) { f32x2 v = {lo, hi}; bf16x2_t b = __builtin_convertvector(v, bf16x2_t); return __builtin_bit_cast(unsigned, b); }
; __global__ void __launch_bounds__(512, 2) fwd_kernel(Params P) {
;     ...
;             { float x[8]; u32x4 raw = (u32x4){0u, 0u, 0u, 0u}; if (lane < 48) raw = *(const u32x4*)(pr + 1536 + lane * 8);
;               float ss = 0.f;
; #pragma unroll
;               for (int i = 0; i < 4; ++i) { x[2 * i] = bf2f(raw[i] & 0xffff); x[2 * i + 1] = bf2f(raw[i] >> 16); ss += x[2 * i] * x[2 * i] + x[2 * i + 1] * x[2 * i + 1]; }
;               const float rstd = 1.0f / sqrtf(wave_sum(ss) * (1.0f / 384.0f) + EPS);
;               if (lane < 48) { const f32x4 g0 = *(const f32x4*)(qng + lane * 8), g1 = *(const f32x4*)(qng + lane * 8 + 4);
;                   u32x4 wv; wv.x = pk2(x[0] * rstd * g0[0], x[1] * rstd * g0[1]); wv.y = pk2(x[2] * rstd * g0[2], x[3] * rstd * g0[3]);
;                   wv.z = pk2(x[4] * rstd * g1[0], x[5] * rstd * g1[1]); wv.w = pk2(x[6] * rstd * g1[2], x[7] * rstd * g1[3]); *(u32x4*)(pr + 1536 + lane * 8) = wv; } }
.LBB0_523:
	s_or_b64 exec, exec, s[12:13]
	s_waitcnt vmcnt(2)
	s_nop 1
	v_mov_b32_e32 v0, v86
	v_mov_b32_e32 v1, v87
	v_mov_b32_e32 v2, v88
	v_mov_b32_e32 v3, v89
	v_lshlrev_b32_e32 v4, 16, v0
	v_and_b32_e32 v5, 0xffff0000, v0
	v_lshlrev_b32_e32 v6, 16, v1
	v_and_b32_e32 v7, 0xffff0000, v1
	v_pk_mul_f32 v[42:43], v[4:5], v[4:5]
	v_pk_mul_f32 v[44:45], v[6:7], v[6:7]
	v_lshlrev_b32_e32 v0, 16, v2
	v_and_b32_e32 v1, 0xffff0000, v2
	v_pk_mul_f32 v[46:47], v[0:1], v[0:1]
	v_lshlrev_b32_e32 v2, 16, v3
	v_and_b32_e32 v3, 0xffff0000, v3
	v_add_f32_e32 v37, v45, v44
	v_add_f32_e32 v41, v43, v42
	v_pk_mul_f32 v[48:49], v[2:3], v[2:3]
	v_add_f32_e32 v37, v41, v37
	v_add_f32_e32 v41, v47, v46
	v_add_f32_e32 v37, v37, v41
	v_add_f32_e32 v41, v49, v48
	v_add_f32_e32 v37, v37, v41
	ds_bpermute_b32 v41, v53, v37
	s_waitcnt lgkmcnt(0)
	v_add_f32_e32 v37, v37, v41
	ds_bpermute_b32 v41, v54, v37
	s_waitcnt lgkmcnt(0)
	v_add_f32_e32 v37, v37, v41
	ds_bpermute_b32 v41, v52, v37
	s_waitcnt lgkmcnt(0)
	v_add_f32_e32 v37, v37, v41
	ds_bpermute_b32 v41, v55, v37
	s_waitcnt lgkmcnt(0)
	v_add_f32_e32 v37, v37, v41
	ds_bpermute_b32 v41, v56, v37
	s_waitcnt lgkmcnt(0)
	v_add_f32_e32 v37, v37, v41
	ds_bpermute_b32 v41, v57, v37
	s_and_saveexec_b64 s[68:69], s[6:7]
	s_cbranch_execz .LBB0_525
	global_load_dwordx4 v[42:45], v[14:15], off
	global_load_dwordx4 v[46:49], v[14:15], off offset:16
	s_waitcnt lgkmcnt(0)
	v_add_f32_e32 v37, v37, v41
	v_fmamk_f32 v37, v37, 0x3b2aaaab, v66
	v_mul_f32_e32 v41, 0x4f800000, v37
	v_cmp_gt_f32_e32 vcc, s59, v37
	s_nop 1
	v_cndmask_b32_e32 v37, v37, v41, vcc
	v_sqrt_f32_e32 v41, v37
	s_nop 0
	v_add_u32_e32 v50, -1, v41
	v_add_u32_e32 v51, 1, v41
	v_fma_f32 v68, -v50, v41, v37
	v_fma_f32 v69, -v51, v41, v37
	v_cmp_ge_f32_e64 s[12:13], 0, v68
	s_nop 1
	v_cndmask_b32_e64 v41, v41, v50, s[12:13]
	v_cmp_lt_f32_e64 s[12:13], 0, v69
	s_nop 1
	v_cndmask_b32_e64 v41, v41, v51, s[12:13]
	v_mul_f32_e32 v50, 0x37800000, v41
	v_cndmask_b32_e32 v41, v41, v50, vcc
	v_cmp_class_f32_e32 vcc, v37, v67
	s_nop 1
	v_cndmask_b32_e32 v37, v41, v37, vcc
	v_div_scale_f32 v41, s[4:5], v37, v37, 1.0
	v_rcp_f32_e32 v50, v41
	v_div_scale_f32 v51, vcc, 1.0, v37, 1.0
	v_fma_f32 v68, -v41, v50, 1.0
	v_fmac_f32_e32 v50, v68, v50
	v_mul_f32_e32 v68, v51, v50
	v_fma_f32 v69, -v41, v68, v51
	v_fmac_f32_e32 v68, v69, v50
	v_fma_f32 v41, -v41, v68, v51
	v_div_fmas_f32 v41, v41, v50, v68
	v_div_fixup_f32 v50, v41, v37, 1.0
	v_pk_mul_f32 v[4:5], v[50:51], v[4:5] op_sel_hi:[0,1]
	v_pk_mul_f32 v[6:7], v[50:51], v[6:7] op_sel_hi:[0,1]
	v_pk_mul_f32 v[0:1], v[50:51], v[0:1] op_sel_hi:[0,1]
	v_pk_mul_f32 v[2:3], v[50:51], v[2:3] op_sel_hi:[0,1]
	s_waitcnt vmcnt(1)
	v_pk_mul_f32 v[4:5], v[4:5], v[42:43]
	v_pk_mul_f32 v[6:7], v[6:7], v[44:45]
	s_waitcnt vmcnt(0)
	v_pk_mul_f32 v[42:43], v[0:1], v[46:47]
	v_pk_mul_f32 v[44:45], v[2:3], v[48:49]
	v_cvt_pk_bf16_f32 v0, v4, v5
	v_cvt_pk_bf16_f32 v1, v6, v7
	v_cvt_pk_bf16_f32 v2, v42, v43
	v_cvt_pk_bf16_f32 v3, v44, v45
	global_store_dwordx4 v[22:23], v[0:3], off offset:3072

; __device__ __forceinline__ float bf2f(unsigned h) { return __uint_as_float(h << 16); }
; __device__ __forceinline__ unsigned pk2(float lo, float hi) { f32x2 v = {lo, hi}; bf16x2_t b = __builtin_convertvector(v, bf16x2_t); return __builtin_bit_cast(unsigned, b); }
; __global__ void __launch_bounds__(512, 2) fwd_kernel(Params P) {
;     ...
;             { float x[8]; u32x4 raw = (u32x4){0u, 0u, 0u, 0u}; if (lane < 32) raw = *(const u32x4*)(pr + 1920 + lane * 8);
;               float ss = 0.f;
; #pragma unroll
;               for (int i = 0; i < 4; ++i) { x[2 * i] = bf2f(raw[i] & 0xffff); x[2 * i + 1] = bf2f(raw[i] >> 16); ss += x[2 * i] * x[2 * i] + x[2 * i + 1] * x[2 * i + 1]; }
;               const float rstd = 1.0f / sqrtf(wave_sum(ss) * (1.0f / 256.0f) + EPS);
;               if (lane < 32) { const f32x4 g0 = *(const f32x4*)(kvg + lane * 8), g1 = *(const f32x4*)(kvg + lane * 8 + 4);
;                   float y[8];
; #pragma unroll
;                   for (int i = 0; i < 4; ++i) { y[i] = x[i] * rstd * g0[i]; y[4 + i] = x[4 + i] * rstd * g1[i]; }
;                   float* fo = OUT + O_LAT + (size_t)row * 256 + lane * 8; __builtin_nontemporal_store((f32x4){y[0], y[1], y[2], y[3]}, (f32x4*)fo); __builtin_nontemporal_store((f32x4){y[4], y[5], y[6], y[7]}, (f32x4*)(fo + 4));
;                   const size_t lr = row < NP ? (size_t)row : (size_t)NP + (size_t)((row - NP) >> 4) * LKSP + 1024 + ((row - NP) & 15);
;                   u32x4 wv; wv.x = pk2(y[0], y[1]); wv.y = pk2(y[2], y[3]); wv.z = pk2(y[4], y[5]); wv.w = pk2(y[6], y[7]); *(u32x4*)(LAT + lr * 256 + lane * 8) = wv; } }
.LBB0_527:
	s_or_b64 exec, exec, s[12:13]
	s_waitcnt vmcnt(1)
	s_nop 1
	v_mov_b32_e32 v0, v90
	v_mov_b32_e32 v1, v91
	v_mov_b32_e32 v2, v92
	v_mov_b32_e32 v3, v93
	v_lshlrev_b32_e32 v4, 16, v0
	v_and_b32_e32 v5, 0xffff0000, v0
	v_lshlrev_b32_e32 v6, 16, v1
	v_and_b32_e32 v7, 0xffff0000, v1
	v_pk_mul_f32 v[42:43], v[4:5], v[4:5]
	v_pk_mul_f32 v[44:45], v[6:7], v[6:7]
	v_lshlrev_b32_e32 v0, 16, v2
	v_and_b32_e32 v1, 0xffff0000, v2
	v_pk_mul_f32 v[46:47], v[0:1], v[0:1]
	v_lshlrev_b32_e32 v2, 16, v3
	v_and_b32_e32 v3, 0xffff0000, v3
	v_add_f32_e32 v37, v44, v45
	s_waitcnt lgkmcnt(0)
	v_add_f32_e32 v41, v42, v43
	v_pk_mul_f32 v[48:49], v[2:3], v[2:3]
	v_add_f32_e32 v37, v41, v37
	v_add_f32_e32 v41, v46, v47
	v_add_f32_e32 v37, v37, v41
	v_add_f32_e32 v41, v48, v49
	v_add_f32_e32 v37, v37, v41
	ds_bpermute_b32 v41, v53, v37
	v_cndmask_b32_e64 v42, 0, 1, s[14:15]
	v_cmp_ne_u32_e64 s[12:13], 1, v42
	s_waitcnt lgkmcnt(0)
	v_add_f32_e32 v37, v37, v41
	ds_bpermute_b32 v41, v54, v37
	s_waitcnt lgkmcnt(0)
	v_add_f32_e32 v37, v37, v41
	ds_bpermute_b32 v41, v52, v37
	s_waitcnt lgkmcnt(0)
	v_add_f32_e32 v37, v37, v41
	ds_bpermute_b32 v41, v55, v37
	s_waitcnt lgkmcnt(0)
	v_add_f32_e32 v37, v37, v41
	ds_bpermute_b32 v41, v56, v37
	s_waitcnt lgkmcnt(0)
	v_add_f32_e32 v37, v37, v41
	ds_bpermute_b32 v41, v57, v37
	s_and_saveexec_b64 s[68:69], s[8:9]
	s_cbranch_execz .LBB0_531
	s_waitcnt lgkmcnt(0)
	v_add_f32_e32 v37, v37, v41
	v_fmamk_f32 v37, v37, 0x3b800000, v66
	v_cmp_gt_f32_e32 vcc, s59, v37
	v_mul_f32_e32 v41, 0x4f800000, v37
	s_nop 0
	v_cndmask_b32_e32 v37, v37, v41, vcc
	v_sqrt_f32_e32 v41, v37
	s_nop 0
	v_add_u32_e32 v42, -1, v41
	v_fma_f32 v43, -v42, v41, v37
	v_cmp_ge_f32_e64 s[14:15], 0, v43
	v_add_u32_e32 v43, 1, v41
	s_nop 0
	v_cndmask_b32_e64 v42, v41, v42, s[14:15]
	v_fma_f32 v41, -v43, v41, v37
	v_cmp_lt_f32_e64 s[14:15], 0, v41
	s_nop 1
	v_cndmask_b32_e64 v41, v42, v43, s[14:15]
	v_mul_f32_e32 v42, 0x37800000, v41
	v_cndmask_b32_e32 v41, v41, v42, vcc
	v_cmp_class_f32_e32 vcc, v37, v67
	s_mov_b64 s[14:15], s[38:39]
	s_nop 0
	v_cndmask_b32_e32 v37, v41, v37, vcc
	v_div_scale_f32 v41, s[4:5], v37, v37, 1.0
	v_rcp_f32_e32 v42, v41
	s_nop 0
	v_fma_f32 v43, -v41, v42, 1.0
	v_fmac_f32_e32 v42, v43, v42
	v_div_scale_f32 v43, vcc, 1.0, v37, 1.0
	v_mul_f32_e32 v44, v43, v42
	v_fma_f32 v45, -v41, v44, v43
	v_fmac_f32_e32 v44, v45, v42
	v_fma_f32 v41, -v41, v44, v43
	v_div_fmas_f32 v41, v41, v42, v44
	global_load_dwordx4 v[42:45], v[16:17], off offset:16
	global_load_dwordx4 v[46:49], v[16:17], off
	v_div_fixup_f32 v50, v41, v37, 1.0
	v_pk_mul_f32 v[0:1], v[50:51], v[0:1] op_sel_hi:[0,1]
	v_pk_mul_f32 v[4:5], v[50:51], v[4:5] op_sel_hi:[0,1]
	v_pk_mul_f32 v[6:7], v[50:51], v[6:7] op_sel_hi:[0,1]
	v_pk_mul_f32 v[2:3], v[50:51], v[2:3] op_sel_hi:[0,1]
	s_waitcnt vmcnt(1)
	v_pk_mul_f32 v[0:1], v[42:43], v[0:1]
	v_lshl_add_u64 v[42:43], s[34:35], 0, v[12:13]
	v_add_co_u32_e32 v42, vcc, 0x10100000, v42
	s_waitcnt vmcnt(0)
	v_pk_mul_f32 v[4:5], v[46:47], v[4:5]
	v_addc_co_u32_e32 v43, vcc, 0, v43, vcc
	v_pk_mul_f32 v[6:7], v[48:49], v[6:7]
	v_pk_mul_f32 v[2:3], v[44:45], v[2:3]
	s_and_b64 vcc, exec, s[12:13]
	global_store_dwordx4 v[42:43], v[4:7], off nt
	global_store_dwordx4 v[42:43], v[0:3], off offset:16 nt
	s_cbranch_vccnz .LBB0_530
	s_add_i32 s3, s60, 0xffff8000
	s_lshr_b32 s3, s3, 4
	s_mul_hi_u32 s5, s3, 0x440
	s_mulk_i32 s3, 0x440
	s_or_b32 s4, s3, s70
	s_lshl_b64 s[4:5], s[4:5], 9
	s_add_u32 s14, s4, 0x1080000
	s_addc_u32 s15, s5, 0

; __device__ __forceinline__ float bf2f(unsigned h) { return __uint_as_float(h << 16); }
; __device__ __forceinline__ unsigned pk2(float lo, float hi) { f32x2 v = {lo, hi}; bf16x2_t b = __builtin_convertvector(v, bf16x2_t); return __builtin_bit_cast(unsigned, b); }
; __global__ void __launch_bounds__(512, 2) fwd_kernel(Params P) {
;     ...
;             { float x[8], y[8]; u32x4 raw = (u32x4){0u, 0u, 0u, 0u}; if (lane < 8) raw = *(const u32x4*)(pr + 2176 + lane * 8);
; #pragma unroll
;               for (int i = 0; i < 4; ++i) { x[2 * i] = bf2f(raw[i] & 0xffff); x[2 * i + 1] = bf2f(raw[i] >> 16); }
; #pragma unroll
;               for (int i = 0; i < 8; ++i) { const float o = __shfl_xor(x[i], 4); y[i] = ishi ? (x[i] * cs[i] + o * sn[i]) : (x[i] * cs[i] - o * sn[i]); }
;               if (lane < 8) { float* fo = OUT + O_KR + (size_t)row * 64 + lane * 8; __builtin_nontemporal_store((f32x4){y[0], y[1], y[2], y[3]}, (f32x4*)fo); __builtin_nontemporal_store((f32x4){y[4], y[5], y[6], y[7]}, (f32x4*)(fo + 4));
;                   const size_t lr = row < NP ? (size_t)row : (size_t)NP + (size_t)((row - NP) >> 4) * LKSP + 1024 + ((row - NP) & 15);
;                   u32x4 wv; wv.x = pk2(y[0], y[1]); wv.y = pk2(y[2], y[3]); wv.z = pk2(y[4], y[5]); wv.w = pk2(y[6], y[7]); *(u32x4*)(KR + lr * 64 + lane * 8) = wv; } }
.LBB0_533:
	s_or_b64 exec, exec, s[14:15]
	s_waitcnt vmcnt(0)
	s_nop 1
	v_mov_b32_e32 v0, v94
	v_mov_b32_e32 v1, v95
	v_mov_b32_e32 v2, v96
	v_mov_b32_e32 v3, v97
	v_lshlrev_b32_e32 v37, 16, v0
	v_and_b32_e32 v50, 0xffff0000, v0
	v_lshlrev_b32_e32 v46, 16, v1
	v_and_b32_e32 v47, 0xffff0000, v1
	v_lshlrev_b32_e32 v4, 16, v2
	v_and_b32_e32 v5, 0xffff0000, v2
	v_lshlrev_b32_e32 v6, 16, v3
	v_and_b32_e32 v7, 0xffff0000, v3
	ds_bpermute_b32 v0, v52, v37
	ds_bpermute_b32 v51, v52, v50
	ds_bpermute_b32 v48, v52, v46
	ds_bpermute_b32 v49, v52, v47
	ds_bpermute_b32 v44, v52, v4
	ds_bpermute_b32 v45, v52, v5
	ds_bpermute_b32 v42, v52, v6
	ds_bpermute_b32 v43, v52, v7
	s_and_saveexec_b64 s[14:15], s[10:11]
	s_cbranch_execz .LBB0_514
	s_waitcnt lgkmcnt(6)
	v_pk_mul_f32 v[2:3], v[38:39], v[50:51]
	s_waitcnt lgkmcnt(2)
	v_pk_mul_f32 v[30:31], v[30:31], v[44:45]
	v_add_f32_e32 v1, v2, v3
	v_sub_f32_e32 v2, v2, v3
	v_cndmask_b32_e64 v1, v1, v2, s[0:1]
	v_pk_mul_f32 v[2:3], v[34:35], v[48:49]
	s_waitcnt lgkmcnt(0)
	v_pk_mul_f32 v[26:27], v[26:27], v[42:43]
	v_pk_fma_f32 v[34:35], v[32:33], v[46:47], v[2:3]
	v_pk_fma_f32 v[2:3], v[32:33], v[46:47], v[2:3] neg_lo:[0,0,1] neg_hi:[0,0,1]
	v_pk_fma_f32 v[32:33], v[28:29], v[4:5], v[30:31]
	v_pk_fma_f32 v[4:5], v[28:29], v[4:5], v[30:31] neg_lo:[0,0,1] neg_hi:[0,0,1]
	v_pk_fma_f32 v[28:29], v[24:25], v[6:7], v[26:27]
	v_pk_fma_f32 v[6:7], v[24:25], v[6:7], v[26:27] neg_lo:[0,0,1] neg_hi:[0,0,1]
	v_lshl_add_u64 v[24:25], s[16:17], 0, v[12:13]
	v_mul_f32_e32 v0, v40, v0
	v_add_co_u32_e32 v24, vcc, 0x12120000, v24
	v_cndmask_b32_e64 v0, v0, -v0, s[0:1]
	s_nop 0
	v_addc_co_u32_e32 v25, vcc, 0, v25, vcc
	v_fmac_f32_e32 v0, v36, v37
	v_cndmask_b32_e64 v3, v35, v3, s[0:1]
	v_cndmask_b32_e64 v2, v34, v2, s[0:1]
	v_cndmask_b32_e64 v5, v33, v5, s[0:1]
	v_cndmask_b32_e64 v4, v32, v4, s[0:1]
	v_cndmask_b32_e64 v7, v29, v7, s[0:1]
	v_cndmask_b32_e64 v6, v28, v6, s[0:1]
	s_and_b64 vcc, exec, s[12:13]
	s_mov_b64 s[12:13], s[60:61]
	global_store_dwordx4 v[24:25], v[0:3], off nt
	global_store_dwordx4 v[24:25], v[4:7], off offset:16 nt
	s_cbranch_vccnz .LBB0_513
	s_add_i32 s3, s60, 0xffff8000
	s_lshr_b32 s3, s3, 4
	s_mul_hi_u32 s4, s3, 0x440
	s_mulk_i32 s3, 0x440
	s_or_b32 s3, s3, s70
	s_add_u32 s12, s3, 0x8400
	s_addc_u32 s13, s4, 0
	s_branch .LBB0_513
